# entry cooperative-groups grid.sync() removed (nothing depends on it; the XCD barrier completes its own census)
# baseline (speedup 1.0000x reference)
; #define LAS __attribute__((address_space(3)))
; __device__ __forceinline__ int opaque_tid() { int t = threadIdx.x; asm volatile("" : "+v"(t)); return t; }
; #define ARGS() (*opaque_kargs())
; #define WSPTR() ({ unsigned char* w_ = ARGS().ws; asm volatile("" : "+s"(w_)); w_; })
; #define G opaque_s(G0)
; #define bx opaque_s(bx0)
; __global__ void __launch_bounds__(NWAVES * 64, 2) mega_fwd(Args args_) {
;     ...
;     if (threadIdx.x == 0) { volatile LAS unsigned* mq0_ = (volatile LAS unsigned*)(ldsl + MISC_OFF); mq0_[8] = 0u; mq0_[9] = 0u; }
;     __syncthreads();
;     (void)xcd_barrier_post((unsigned*)(ARGS().ws + WS_BAR), (volatile LAS unsigned*)(ldsl + MISC_OFF) + 8);
;     grid.sync();
;     const int G0 = gridDim.x, bx0 = blockIdx.x;
;     ...
;     {
;         unsigned char* ws = WSPTR();
;         const int tid = opaque_tid(), lane = tid & 63, wave = __builtin_amdgcn_readfirstlane(tid >> 6);
;         const int gw = bx * NWAVES + wave, NGW = G * NWAVES;
;         unsigned* ctl = (unsigned*)(ws + WS_CTL); float* ssq = (float*)(ws + WS_SSQ);
;         float* cosT = (float*)(ws + WS_COS); float* sinT = (float*)(ws + WS_SIN);
;         bf16* XB = (bf16*)(ws + WS_XB);
;         if (bx == 0) for (int i = tid; i < 4096; i += NWAVES * 64) ctl[i] = 0u;
.LBB0_15:
	s_mov_b64 s[2:3], s[0:1]
	s_barrier
	s_load_dwordx2 s[34:35], s[2:3], 0xe0
	v_mov_b32_e32 v64, v230
	s_mov_b32 s12, s30
	s_mov_b32 s22, s36
	s_mov_b32 s2, s30
	s_waitcnt lgkmcnt(0)
	s_cmp_eq_u32 s2, 0
	s_movk_i32 s4, 0x1000
	s_cselect_b64 s[2:3], -1, 0
	v_cmp_gt_i32_e32 vcc, s4, v64
	v_readfirstlane_b32 s13, v64
	s_and_b64 s[4:5], s[2:3], vcc
	s_and_saveexec_b64 s[2:3], s[4:5]
	s_cbranch_execz .LBB0_23
	v_max_i32_e32 v0, 0xe00, v64
	v_sub_u32_e32 v0, v0, v64
	s_movk_i32 s4, 0x1ff
	v_add_u32_e32 v1, 0x1ff, v0
	v_cmp_lt_u32_e32 vcc, s4, v1
	s_mov_b64 s[6:7], -1
	v_mov_b32_e32 v0, v64
	s_and_saveexec_b64 s[4:5], vcc
	s_cbranch_execz .LBB0_20
	v_lshrrev_b32_e32 v0, 9, v1
	v_add_u32_e32 v2, 1, v0
	v_and_b32_e32 v3, 0xfffffe, v2
	v_add_u32_e32 v65, 0x200, v64
	s_mov_b64 s[6:7], 0
	v_mov_b32_e32 v4, 0
	v_mov_b32_e32 v5, v3
	v_mov_b64_e32 v[0:1], v[64:65]
